# speedup vs baseline: 1.0761x; 1.0194x over previous
; template <class LA>
; DI void gemm_tile(const LA& la, int m0, const u16* __restrict__ Bm, long ldb, int K, f32x16 (&acc)[2][2], char* lds, int tid) {
;     ...
;   const int arow = (wm * 64 + (lane & 31)) * 144 + (lane >> 5) * 16;
;   const int brow = 18432 + (wn * 64 + (lane & 31)) * 144 + (lane >> 5) * 16;
;   char* lds0 = lds;
;   char* lds1 = lds + 36864;
;   __syncthreads();
;   GT_LOAD(p, 0)
;   if (nk > 1) { GT_LOAD(q, 64) }
;   GT_STORE(p, lds0)
;   __syncthreads();
; #pragma unroll 1
;   for (int kt = 0; kt < nk; kt += 2) {
;     if (kt + 2 < nk) { GT_LOAD(p, (kt + 2) * 64) }
;     GT_COMPUTE(lds0)
;     if (kt + 1 < nk) { GT_STORE(q, lds1) }
;     __syncthreads();
;     if (kt + 1 >= nk) break;
;     if (kt + 3 < nk) { GT_LOAD(q, (kt + 3) * 64) }
;     GT_COMPUTE(lds1)
;     if (kt + 2 < nk) { GT_STORE(p, lds0) }
;     __syncthreads();
;   }
.Lp7n_loop:
	ds_read_b128 v[236:239], v136 offset:32
	ds_read_b128 v[240:243], v136 offset:4640
	ds_read_b128 v[244:247], v137 offset:18464
	ds_read_b128 v[248:251], v137 offset:23072
	s_waitcnt lgkmcnt(4)
	v_mfma_f32_32x32x16_bf16 v[48:63], v[220:223], v[228:231], v[48:63]
	global_load_dwordx4 v[64:67], v146, s[30:31] offset:256
	v_mfma_f32_32x32x16_bf16 v[32:47], v[220:223], v[232:235], v[32:47]
	global_load_dwordx4 v[68:71], v147, s[30:31] offset:256
	v_mfma_f32_32x32x16_bf16 v[16:31], v[224:227], v[228:231], v[16:31]
	global_load_dwordx4 v[72:75], v172, s[30:31] offset:256
	ds_read_b128 v[164:167], v136 offset:64
	ds_read_b128 v[168:171], v136 offset:4672
	s_waitcnt vmcnt(3)
	v_mfma_f32_32x32x16_bf16 v[0:15], v[224:227], v[232:235], v[0:15]
	global_load_dwordx4 v[76:79], v173, s[30:31] offset:256
	ds_read_b128 v[156:159], v137 offset:18496
	ds_read_b128 v[160:163], v137 offset:23104
	ds_write_b128 v219, v[84:87] offset:36864
	s_waitcnt lgkmcnt(5)
	v_mfma_f32_32x32x16_bf16 v[48:63], v[236:239], v[244:247], v[48:63]
	global_load_dwordx4 v[80:83], v200, s[34:35] offset:256
	ds_write_b128 v219, v[92:95] offset:41472
	v_mfma_f32_32x32x16_bf16 v[32:47], v[236:239], v[248:251], v[32:47]
	global_load_dwordx4 v[88:91], v201, s[34:35] offset:256
	ds_write_b128 v219, v[100:103] offset:46080
	v_mfma_f32_32x32x16_bf16 v[16:31], v[240:243], v[244:247], v[16:31]
	global_load_dwordx4 v[96:99], v252, s[34:35] offset:256
	ds_write_b128 v219, v[108:111] offset:50688
	ds_read_b128 v[220:223], v136 offset:96
	ds_read_b128 v[224:227], v136 offset:4704
	v_mfma_f32_32x32x16_bf16 v[0:15], v[240:243], v[248:251], v[0:15]
	global_load_dwordx4 v[104:107], v253, s[34:35] offset:256
	ds_write_b128 v219, v[112:115] offset:55296
	ds_read_b128 v[228:231], v137 offset:18528
	ds_read_b128 v[232:235], v137 offset:23136
	s_waitcnt lgkmcnt(9)
	v_mfma_f32_32x32x16_bf16 v[48:63], v[164:167], v[156:159], v[48:63]
	ds_write_b128 v219, v[116:119] offset:59904
	v_mfma_f32_32x32x16_bf16 v[32:47], v[164:167], v[160:163], v[32:47]
	ds_write_b128 v219, v[120:123] offset:64512
	v_mfma_f32_32x32x16_bf16 v[16:31], v[168:171], v[156:159], v[16:31]
	ds_write_b128 v218, v[124:127] offset:13824
	v_mfma_f32_32x32x16_bf16 v[0:15], v[168:171], v[160:163], v[0:15]
	s_waitcnt lgkmcnt(0)
	s_barrier
	v_mfma_f32_32x32x16_bf16 v[48:63], v[220:223], v[228:231], v[48:63]
	ds_read_b128 v[236:239], v136 offset:36864
	ds_read_b128 v[240:243], v136 offset:41472
	v_mfma_f32_32x32x16_bf16 v[32:47], v[220:223], v[232:235], v[32:47]
	ds_read_b128 v[244:247], v137 offset:55296
	ds_read_b128 v[248:251], v137 offset:59904
	v_mfma_f32_32x32x16_bf16 v[16:31], v[224:227], v[228:231], v[16:31]
	v_mfma_f32_32x32x16_bf16 v[0:15], v[224:227], v[232:235], v[0:15]
	ds_read_b128 v[164:167], v136 offset:36896
	ds_read_b128 v[168:171], v136 offset:41504
	ds_read_b128 v[156:159], v137 offset:55328
	ds_read_b128 v[160:163], v137 offset:59936
	s_waitcnt lgkmcnt(4)
	v_mfma_f32_32x32x16_bf16 v[48:63], v[236:239], v[244:247], v[48:63]
	global_load_dwordx4 v[84:87], v146, s[30:31] offset:384
	v_mfma_f32_32x32x16_bf16 v[32:47], v[236:239], v[248:251], v[32:47]
	global_load_dwordx4 v[92:95], v147, s[30:31] offset:384
	v_mfma_f32_32x32x16_bf16 v[16:31], v[240:243], v[244:247], v[16:31]
	global_load_dwordx4 v[100:103], v172, s[30:31] offset:384
	ds_read_b128 v[220:223], v136 offset:36928
	ds_read_b128 v[224:227], v136 offset:41536
	s_waitcnt vmcnt(3)
	v_mfma_f32_32x32x16_bf16 v[0:15], v[240:243], v[248:251], v[0:15]
	global_load_dwordx4 v[108:111], v173, s[30:31] offset:384
	ds_read_b128 v[228:231], v137 offset:55360
	ds_read_b128 v[232:235], v137 offset:59968
	ds_write_b128 v219, v[64:67]
	s_waitcnt lgkmcnt(5)
	v_mfma_f32_32x32x16_bf16 v[48:63], v[164:167], v[156:159], v[48:63]
	global_load_dwordx4 v[112:115], v200, s[34:35] offset:384
	ds_write_b128 v219, v[68:71] offset:4608
	v_mfma_f32_32x32x16_bf16 v[32:47], v[164:167], v[160:163], v[32:47]
	global_load_dwordx4 v[116:119], v201, s[34:35] offset:384
	ds_write_b128 v219, v[72:75] offset:9216
	v_mfma_f32_32x32x16_bf16 v[16:31], v[168:171], v[156:159], v[16:31]
	global_load_dwordx4 v[120:123], v252, s[34:35] offset:384
	ds_write_b128 v219, v[76:79] offset:13824
	ds_read_b128 v[236:239], v136 offset:36960
	ds_read_b128 v[240:243], v136 offset:41568
	v_mfma_f32_32x32x16_bf16 v[0:15], v[168:171], v[160:163], v[0:15]
	global_load_dwordx4 v[124:127], v253, s[34:35] offset:384
	ds_write_b128 v219, v[80:83] offset:18432
	ds_read_b128 v[244:247], v137 offset:55392
	ds_read_b128 v[248:251], v137 offset:60000
	s_waitcnt lgkmcnt(9)
	v_mfma_f32_32x32x16_bf16 v[48:63], v[220:223], v[228:231], v[48:63]
	ds_write_b128 v219, v[88:91] offset:23040
	v_mfma_f32_32x32x16_bf16 v[32:47], v[220:223], v[232:235], v[32:47]
	ds_write_b128 v219, v[96:99] offset:27648
	v_mfma_f32_32x32x16_bf16 v[16:31], v[224:227], v[228:231], v[16:31]
	ds_write_b128 v219, v[104:107] offset:32256
	v_mfma_f32_32x32x16_bf16 v[0:15], v[224:227], v[232:235], v[0:15]
	s_waitcnt lgkmcnt(0)
	s_barrier
; template <class LA>
; DI void gemm_tile(const LA& la, int m0, const u16* __restrict__ Bm, long ldb, int K, f32x16 (&acc)[2][2], char* lds, int tid) {
;     ...
;   const int arow = (wm * 64 + (lane & 31)) * 144 + (lane >> 5) * 16;
;   const int brow = 18432 + (wn * 64 + (lane & 31)) * 144 + (lane >> 5) * 16;
;   char* lds0 = lds;
;   char* lds1 = lds + 36864;
;   __syncthreads();
;   GT_LOAD(p, 0)
;   if (nk > 1) { GT_LOAD(q, 64) }
;   GT_STORE(p, lds0)
;   __syncthreads();
; #pragma unroll 1
;   for (int kt = 0; kt < nk; kt += 2) {
;     if (kt + 2 < nk) { GT_LOAD(p, (kt + 2) * 64) }
;     GT_COMPUTE(lds0)
;     if (kt + 1 < nk) { GT_STORE(q, lds1) }
;     __syncthreads();
;     if (kt + 1 >= nk) break;
;     if (kt + 3 < nk) { GT_LOAD(q, (kt + 3) * 64) }
;     GT_COMPUTE(lds1)
;     if (kt + 2 < nk) { GT_STORE(p, lds0) }
;     __syncthreads();
;   }
	v_mfma_f32_32x32x16_bf16 v[48:63], v[236:239], v[244:247], v[48:63]
	ds_read_b128 v[164:167], v136
	ds_read_b128 v[168:171], v136 offset:4608
	v_mfma_f32_32x32x16_bf16 v[32:47], v[236:239], v[248:251], v[32:47]
	ds_read_b128 v[156:159], v137 offset:18432
	ds_read_b128 v[160:163], v137 offset:23040
	v_mfma_f32_32x32x16_bf16 v[16:31], v[240:243], v[244:247], v[16:31]
	v_mfma_f32_32x32x16_bf16 v[0:15], v[240:243], v[248:251], v[0:15]
	ds_read_b128 v[220:223], v136 offset:32
	ds_read_b128 v[224:227], v136 offset:4640
	ds_read_b128 v[228:231], v137 offset:18464
	ds_read_b128 v[232:235], v137 offset:23072
	s_waitcnt lgkmcnt(4)
	v_mfma_f32_32x32x16_bf16 v[48:63], v[164:167], v[156:159], v[48:63]
	global_load_dwordx4 v[64:67], v146, s[30:31] offset:512
	v_mfma_f32_32x32x16_bf16 v[32:47], v[164:167], v[160:163], v[32:47]
	global_load_dwordx4 v[68:71], v147, s[30:31] offset:512
	v_mfma_f32_32x32x16_bf16 v[16:31], v[168:171], v[156:159], v[16:31]
	global_load_dwordx4 v[72:75], v172, s[30:31] offset:512
	ds_read_b128 v[236:239], v136 offset:64
	ds_read_b128 v[240:243], v136 offset:4672
	s_waitcnt vmcnt(3)
	v_mfma_f32_32x32x16_bf16 v[0:15], v[168:171], v[160:163], v[0:15]
	global_load_dwordx4 v[76:79], v173, s[30:31] offset:512
	ds_read_b128 v[244:247], v137 offset:18496
	ds_read_b128 v[248:251], v137 offset:23104
	ds_write_b128 v219, v[84:87] offset:36864
	s_waitcnt lgkmcnt(5)
	v_mfma_f32_32x32x16_bf16 v[48:63], v[220:223], v[228:231], v[48:63]
	global_load_dwordx4 v[80:83], v200, s[34:35] offset:512
	ds_write_b128 v219, v[92:95] offset:41472
	v_mfma_f32_32x32x16_bf16 v[32:47], v[220:223], v[232:235], v[32:47]
	global_load_dwordx4 v[88:91], v201, s[34:35] offset:512
	ds_write_b128 v219, v[100:103] offset:46080
	v_mfma_f32_32x32x16_bf16 v[16:31], v[224:227], v[228:231], v[16:31]
	global_load_dwordx4 v[96:99], v252, s[34:35] offset:512
	ds_write_b128 v219, v[108:111] offset:50688
	ds_read_b128 v[164:167], v136 offset:96
	ds_read_b128 v[168:171], v136 offset:4704
	v_mfma_f32_32x32x16_bf16 v[0:15], v[224:227], v[232:235], v[0:15]
	global_load_dwordx4 v[104:107], v253, s[34:35] offset:512
	ds_write_b128 v219, v[112:115] offset:55296
	ds_read_b128 v[156:159], v137 offset:18528
	ds_read_b128 v[160:163], v137 offset:23136
	s_waitcnt lgkmcnt(9)
	v_mfma_f32_32x32x16_bf16 v[48:63], v[236:239], v[244:247], v[48:63]
	ds_write_b128 v219, v[116:119] offset:59904
	v_mfma_f32_32x32x16_bf16 v[32:47], v[236:239], v[248:251], v[32:47]
	ds_write_b128 v219, v[120:123] offset:64512
	v_mfma_f32_32x32x16_bf16 v[16:31], v[240:243], v[244:247], v[16:31]
	ds_write_b128 v218, v[124:127] offset:13824
	v_mfma_f32_32x32x16_bf16 v[0:15], v[240:243], v[248:251], v[0:15]
	s_waitcnt lgkmcnt(0)
	s_barrier
	v_mfma_f32_32x32x16_bf16 v[48:63], v[164:167], v[156:159], v[48:63]
	ds_read_b128 v[220:223], v136 offset:36864
	ds_read_b128 v[224:227], v136 offset:41472
	v_mfma_f32_32x32x16_bf16 v[32:47], v[164:167], v[160:163], v[32:47]
	ds_read_b128 v[228:231], v137 offset:55296
	ds_read_b128 v[232:235], v137 offset:59904
	v_mfma_f32_32x32x16_bf16 v[16:31], v[168:171], v[156:159], v[16:31]
	v_mfma_f32_32x32x16_bf16 v[0:15], v[168:171], v[160:163], v[0:15]
	ds_read_b128 v[236:239], v136 offset:36896
	ds_read_b128 v[240:243], v136 offset:41504
	ds_read_b128 v[244:247], v137 offset:55328
	ds_read_b128 v[248:251], v137 offset:59936
	s_waitcnt lgkmcnt(4)
	v_mfma_f32_32x32x16_bf16 v[48:63], v[220:223], v[228:231], v[48:63]
	global_load_dwordx4 v[84:87], v146, s[30:31] offset:640
	v_mfma_f32_32x32x16_bf16 v[32:47], v[220:223], v[232:235], v[32:47]
	global_load_dwordx4 v[92:95], v147, s[30:31] offset:640
	v_mfma_f32_32x32x16_bf16 v[16:31], v[224:227], v[228:231], v[16:31]
	global_load_dwordx4 v[100:103], v172, s[30:31] offset:640
	ds_read_b128 v[164:167], v136 offset:36928
	ds_read_b128 v[168:171], v136 offset:41536
	s_waitcnt vmcnt(3)
	v_mfma_f32_32x32x16_bf16 v[0:15], v[224:227], v[232:235], v[0:15]
	global_load_dwordx4 v[108:111], v173, s[30:31] offset:640
	ds_read_b128 v[156:159], v137 offset:55360
	ds_read_b128 v[160:163], v137 offset:59968
	ds_write_b128 v219, v[64:67]
	s_waitcnt lgkmcnt(5)
	v_mfma_f32_32x32x16_bf16 v[48:63], v[236:239], v[244:247], v[48:63]
	global_load_dwordx4 v[112:115], v200, s[34:35] offset:640
	ds_write_b128 v219, v[68:71] offset:4608
	v_mfma_f32_32x32x16_bf16 v[32:47], v[236:239], v[248:251], v[32:47]
	global_load_dwordx4 v[116:119], v201, s[34:35] offset:640
	ds_write_b128 v219, v[72:75] offset:9216
	v_mfma_f32_32x32x16_bf16 v[16:31], v[240:243], v[244:247], v[16:31]
	global_load_dwordx4 v[120:123], v252, s[34:35] offset:640
	ds_write_b128 v219, v[76:79] offset:13824
	ds_read_b128 v[220:223], v136 offset:36960
	ds_read_b128 v[224:227], v136 offset:41568
	v_mfma_f32_32x32x16_bf16 v[0:15], v[240:243], v[248:251], v[0:15]
	global_load_dwordx4 v[124:127], v253, s[34:35] offset:640
	ds_write_b128 v219, v[80:83] offset:18432
	ds_read_b128 v[228:231], v137 offset:55392
	ds_read_b128 v[232:235], v137 offset:60000
	s_waitcnt lgkmcnt(9)
	v_mfma_f32_32x32x16_bf16 v[48:63], v[164:167], v[156:159], v[48:63]
	ds_write_b128 v219, v[88:91] offset:23040
	v_mfma_f32_32x32x16_bf16 v[32:47], v[164:167], v[160:163], v[32:47]
	ds_write_b128 v219, v[96:99] offset:27648
	v_mfma_f32_32x32x16_bf16 v[16:31], v[168:171], v[156:159], v[16:31]
	ds_write_b128 v219, v[104:107] offset:32256
	v_mfma_f32_32x32x16_bf16 v[0:15], v[168:171], v[160:163], v[0:15]
	s_waitcnt lgkmcnt(0)
	s_barrier
; template <class LA>
; DI void gemm_tile(const LA& la, int m0, const u16* __restrict__ Bm, long ldb, int K, f32x16 (&acc)[2][2], char* lds, int tid) {
;     ...
;   const int arow = (wm * 64 + (lane & 31)) * 144 + (lane >> 5) * 16;
;   const int brow = 18432 + (wn * 64 + (lane & 31)) * 144 + (lane >> 5) * 16;
;   char* lds0 = lds;
;   char* lds1 = lds + 36864;
;   __syncthreads();
;   GT_LOAD(p, 0)
;   if (nk > 1) { GT_LOAD(q, 64) }
;   GT_STORE(p, lds0)
;   __syncthreads();
; #pragma unroll 1
;   for (int kt = 0; kt < nk; kt += 2) {
;     if (kt + 2 < nk) { GT_LOAD(p, (kt + 2) * 64) }
;     GT_COMPUTE(lds0)
;     if (kt + 1 < nk) { GT_STORE(q, lds1) }
;     __syncthreads();
;     if (kt + 1 >= nk) break;
;     if (kt + 3 < nk) { GT_LOAD(q, (kt + 3) * 64) }
;     GT_COMPUTE(lds1)
;     if (kt + 2 < nk) { GT_STORE(p, lds0) }
;     __syncthreads();
;   }
	v_mfma_f32_32x32x16_bf16 v[48:63], v[220:223], v[228:231], v[48:63]
	ds_read_b128 v[236:239], v136
	ds_read_b128 v[240:243], v136 offset:4608
	v_mfma_f32_32x32x16_bf16 v[32:47], v[220:223], v[232:235], v[32:47]
	ds_read_b128 v[244:247], v137 offset:18432
	ds_read_b128 v[248:251], v137 offset:23040
	v_mfma_f32_32x32x16_bf16 v[16:31], v[224:227], v[228:231], v[16:31]
	v_mfma_f32_32x32x16_bf16 v[0:15], v[224:227], v[232:235], v[0:15]
	ds_read_b128 v[164:167], v136 offset:32
	ds_read_b128 v[168:171], v136 offset:4640
	ds_read_b128 v[156:159], v137 offset:18464
	ds_read_b128 v[160:163], v137 offset:23072
	s_waitcnt lgkmcnt(4)
	v_mfma_f32_32x32x16_bf16 v[48:63], v[236:239], v[244:247], v[48:63]
	global_load_dwordx4 v[64:67], v146, s[30:31] offset:768
	v_mfma_f32_32x32x16_bf16 v[32:47], v[236:239], v[248:251], v[32:47]
	global_load_dwordx4 v[68:71], v147, s[30:31] offset:768
	v_mfma_f32_32x32x16_bf16 v[16:31], v[240:243], v[244:247], v[16:31]
	global_load_dwordx4 v[72:75], v172, s[30:31] offset:768
	ds_read_b128 v[220:223], v136 offset:64
	ds_read_b128 v[224:227], v136 offset:4672
	s_waitcnt vmcnt(3)
	v_mfma_f32_32x32x16_bf16 v[0:15], v[240:243], v[248:251], v[0:15]
	global_load_dwordx4 v[76:79], v173, s[30:31] offset:768
	ds_read_b128 v[228:231], v137 offset:18496
	ds_read_b128 v[232:235], v137 offset:23104
	ds_write_b128 v219, v[84:87] offset:36864
	s_waitcnt lgkmcnt(5)
	v_mfma_f32_32x32x16_bf16 v[48:63], v[164:167], v[156:159], v[48:63]
	global_load_dwordx4 v[80:83], v200, s[34:35] offset:768
	ds_write_b128 v219, v[92:95] offset:41472
	v_mfma_f32_32x32x16_bf16 v[32:47], v[164:167], v[160:163], v[32:47]
	global_load_dwordx4 v[88:91], v201, s[34:35] offset:768
	ds_write_b128 v219, v[100:103] offset:46080
	v_mfma_f32_32x32x16_bf16 v[16:31], v[168:171], v[156:159], v[16:31]
	global_load_dwordx4 v[96:99], v252, s[34:35] offset:768
	ds_write_b128 v219, v[108:111] offset:50688
	ds_read_b128 v[236:239], v136 offset:96
	ds_read_b128 v[240:243], v136 offset:4704
	v_mfma_f32_32x32x16_bf16 v[0:15], v[168:171], v[160:163], v[0:15]
	global_load_dwordx4 v[104:107], v253, s[34:35] offset:768
	ds_write_b128 v219, v[112:115] offset:55296
	ds_read_b128 v[244:247], v137 offset:18528
	ds_read_b128 v[248:251], v137 offset:23136
	s_waitcnt lgkmcnt(9)
	v_mfma_f32_32x32x16_bf16 v[48:63], v[220:223], v[228:231], v[48:63]
	ds_write_b128 v219, v[116:119] offset:59904
	v_mfma_f32_32x32x16_bf16 v[32:47], v[220:223], v[232:235], v[32:47]
	ds_write_b128 v219, v[120:123] offset:64512
	v_mfma_f32_32x32x16_bf16 v[16:31], v[224:227], v[228:231], v[16:31]
	ds_write_b128 v218, v[124:127] offset:13824
	v_mfma_f32_32x32x16_bf16 v[0:15], v[224:227], v[232:235], v[0:15]
	s_waitcnt lgkmcnt(0)
	s_barrier
	v_mfma_f32_32x32x16_bf16 v[48:63], v[236:239], v[244:247], v[48:63]
	ds_read_b128 v[164:167], v136 offset:36864
	ds_read_b128 v[168:171], v136 offset:41472
	v_mfma_f32_32x32x16_bf16 v[32:47], v[236:239], v[248:251], v[32:47]
	ds_read_b128 v[156:159], v137 offset:55296
	ds_read_b128 v[160:163], v137 offset:59904
	v_mfma_f32_32x32x16_bf16 v[16:31], v[240:243], v[244:247], v[16:31]
	v_mfma_f32_32x32x16_bf16 v[0:15], v[240:243], v[248:251], v[0:15]
	ds_read_b128 v[220:223], v136 offset:36896
	ds_read_b128 v[224:227], v136 offset:41504
	ds_read_b128 v[228:231], v137 offset:55328
	ds_read_b128 v[232:235], v137 offset:59936
	s_waitcnt lgkmcnt(4)
	v_mfma_f32_32x32x16_bf16 v[48:63], v[164:167], v[156:159], v[48:63]
	global_load_dwordx4 v[84:87], v146, s[30:31] offset:896
	v_mfma_f32_32x32x16_bf16 v[32:47], v[164:167], v[160:163], v[32:47]
	global_load_dwordx4 v[92:95], v147, s[30:31] offset:896
	v_mfma_f32_32x32x16_bf16 v[16:31], v[168:171], v[156:159], v[16:31]
	global_load_dwordx4 v[100:103], v172, s[30:31] offset:896
	ds_read_b128 v[236:239], v136 offset:36928
	ds_read_b128 v[240:243], v136 offset:41536
	s_waitcnt vmcnt(3)
	v_mfma_f32_32x32x16_bf16 v[0:15], v[168:171], v[160:163], v[0:15]
	global_load_dwordx4 v[108:111], v173, s[30:31] offset:896
	ds_read_b128 v[244:247], v137 offset:55360
	ds_read_b128 v[248:251], v137 offset:59968
	ds_write_b128 v219, v[64:67]
	s_waitcnt lgkmcnt(5)
	v_mfma_f32_32x32x16_bf16 v[48:63], v[220:223], v[228:231], v[48:63]
	global_load_dwordx4 v[112:115], v200, s[34:35] offset:896
	ds_write_b128 v219, v[68:71] offset:4608
	v_mfma_f32_32x32x16_bf16 v[32:47], v[220:223], v[232:235], v[32:47]
	global_load_dwordx4 v[116:119], v201, s[34:35] offset:896
	ds_write_b128 v219, v[72:75] offset:9216
	v_mfma_f32_32x32x16_bf16 v[16:31], v[224:227], v[228:231], v[16:31]
	global_load_dwordx4 v[120:123], v252, s[34:35] offset:896
	ds_write_b128 v219, v[76:79] offset:13824
	ds_read_b128 v[164:167], v136 offset:36960
	ds_read_b128 v[168:171], v136 offset:41568
	v_mfma_f32_32x32x16_bf16 v[0:15], v[224:227], v[232:235], v[0:15]
	global_load_dwordx4 v[124:127], v253, s[34:35] offset:896
	ds_write_b128 v219, v[80:83] offset:18432
	ds_read_b128 v[156:159], v137 offset:55392
	ds_read_b128 v[160:163], v137 offset:60000
	s_waitcnt lgkmcnt(9)
	v_mfma_f32_32x32x16_bf16 v[48:63], v[236:239], v[244:247], v[48:63]
	ds_write_b128 v219, v[88:91] offset:23040
	v_mfma_f32_32x32x16_bf16 v[32:47], v[236:239], v[248:251], v[32:47]
	ds_write_b128 v219, v[96:99] offset:27648
	v_mfma_f32_32x32x16_bf16 v[16:31], v[240:243], v[244:247], v[16:31]
	ds_write_b128 v219, v[104:107] offset:32256
	v_mfma_f32_32x32x16_bf16 v[0:15], v[240:243], v[248:251], v[0:15]
	s_waitcnt lgkmcnt(0)
	s_barrier
	v_mfma_f32_32x32x16_bf16 v[48:63], v[164:167], v[156:159], v[48:63]
	ds_read_b128 v[220:223], v136
	ds_read_b128 v[224:227], v136 offset:4608
	v_mfma_f32_32x32x16_bf16 v[32:47], v[164:167], v[160:163], v[32:47]
	ds_read_b128 v[228:231], v137 offset:18432
	ds_read_b128 v[232:235], v137 offset:23040
	v_mfma_f32_32x32x16_bf16 v[16:31], v[168:171], v[156:159], v[16:31]
	v_mfma_f32_32x32x16_bf16 v[0:15], v[168:171], v[160:163], v[0:15]
	s_add_u32 s30, s30, 0x300
	s_addc_u32 s31, s31, 0
	s_add_u32 s34, s34, 0x300
	s_addc_u32 s35, s35, 0
	s_add_i32 s7, s7, 6
	s_cmp_lt_u32 s7, 30
	s_cbranch_scc1 .Lp7n_loop
	s_branch .LBB0_280

; template <class LA>
; DI void gemm_tile(const LA& la, int m0, const u16* __restrict__ Bm, long ldb, int K, f32x16 (&acc)[2][2], char* lds, int tid) {
;     ...
;   const int arow = (wm * 64 + (lane & 31)) * 144 + (lane >> 5) * 16;
;   const int brow = 18432 + (wn * 64 + (lane & 31)) * 144 + (lane >> 5) * 16;
;   char* lds0 = lds;
;   char* lds1 = lds + 36864;
;   __syncthreads();
;   GT_LOAD(p, 0)
;   if (nk > 1) { GT_LOAD(q, 64) }
;   GT_STORE(p, lds0)
;   __syncthreads();
; #pragma unroll 1
;   for (int kt = 0; kt < nk; kt += 2) {
;     if (kt + 2 < nk) { GT_LOAD(p, (kt + 2) * 64) }
;     GT_COMPUTE(lds0)
;     if (kt + 1 < nk) { GT_STORE(q, lds1) }
;     __syncthreads();
;     if (kt + 1 >= nk) break;
;     if (kt + 3 < nk) { GT_LOAD(q, (kt + 3) * 64) }
;     GT_COMPUTE(lds1)
;     if (kt + 2 < nk) { GT_STORE(p, lds0) }
;     __syncthreads();
;   }
.Lp6n_loop:
	ds_read_b128 v[210:213], v136 offset:32
	ds_read_b128 v[214:217], v136 offset:4640
	ds_read_b128 v[218:221], v131 offset:18464
	ds_read_b128 v[222:225], v131 offset:23072
	s_waitcnt lgkmcnt(4)
	v_mfma_f32_32x32x16_bf16 v[48:63], v[162:165], v[174:177], v[48:63]
	global_load_dwordx4 v[64:67], v156, s[30:31] offset:256
	v_mfma_f32_32x32x16_bf16 v[32:47], v[162:165], v[206:209], v[32:47]
	global_load_dwordx4 v[68:71], v157, s[30:31] offset:256
	v_mfma_f32_32x32x16_bf16 v[16:31], v[166:169], v[174:177], v[16:31]
	global_load_dwordx4 v[72:75], v158, s[30:31] offset:256
	ds_read_b128 v[226:229], v136 offset:64
	ds_read_b128 v[230:233], v136 offset:4672
	s_waitcnt vmcnt(3)
	v_mfma_f32_32x32x16_bf16 v[0:15], v[166:169], v[206:209], v[0:15]
	global_load_dwordx4 v[76:79], v159, s[30:31] offset:256
	ds_read_b128 v[234:237], v131 offset:18496
	ds_read_b128 v[238:241], v131 offset:23104
	ds_write_b128 v173, v[84:87] offset:36864
	s_waitcnt lgkmcnt(5)
	v_mfma_f32_32x32x16_bf16 v[48:63], v[210:213], v[218:221], v[48:63]
	global_load_dwordx4 v[80:83], v160, s[34:35] offset:256
	ds_write_b128 v173, v[92:95] offset:41472
	v_mfma_f32_32x32x16_bf16 v[32:47], v[210:213], v[222:225], v[32:47]
	global_load_dwordx4 v[88:91], v161, s[34:35] offset:256
	ds_write_b128 v173, v[100:103] offset:46080
	v_mfma_f32_32x32x16_bf16 v[16:31], v[214:217], v[218:221], v[16:31]
	global_load_dwordx4 v[96:99], v170, s[34:35] offset:256
	ds_write_b128 v173, v[108:111] offset:50688
	ds_read_b128 v[242:245], v136 offset:96
	ds_read_b128 v[246:249], v136 offset:4704
	v_mfma_f32_32x32x16_bf16 v[0:15], v[214:217], v[222:225], v[0:15]
	global_load_dwordx4 v[104:107], v171, s[34:35] offset:256
	ds_write_b128 v173, v[112:115] offset:55296
	ds_read_b128 v[250:253], v131 offset:18528
	ds_read_b128 v[144:147], v131 offset:23136
	s_waitcnt lgkmcnt(9)
	v_mfma_f32_32x32x16_bf16 v[48:63], v[226:229], v[234:237], v[48:63]
	ds_write_b128 v173, v[116:119] offset:59904
	v_mfma_f32_32x32x16_bf16 v[32:47], v[226:229], v[238:241], v[32:47]
	ds_write_b128 v173, v[120:123] offset:64512
	v_mfma_f32_32x32x16_bf16 v[16:31], v[230:233], v[234:237], v[16:31]
	ds_write_b128 v172, v[124:127] offset:13824
	v_mfma_f32_32x32x16_bf16 v[0:15], v[230:233], v[238:241], v[0:15]
	s_waitcnt lgkmcnt(0)
	s_barrier
	v_mfma_f32_32x32x16_bf16 v[48:63], v[242:245], v[250:253], v[48:63]
	ds_read_b128 v[162:165], v136 offset:36864
	ds_read_b128 v[166:169], v136 offset:41472
	v_mfma_f32_32x32x16_bf16 v[32:47], v[242:245], v[144:147], v[32:47]
	ds_read_b128 v[174:177], v131 offset:55296
	ds_read_b128 v[206:209], v131 offset:59904
	v_mfma_f32_32x32x16_bf16 v[16:31], v[246:249], v[250:253], v[16:31]
	v_mfma_f32_32x32x16_bf16 v[0:15], v[246:249], v[144:147], v[0:15]
	ds_read_b128 v[210:213], v136 offset:36896
	ds_read_b128 v[214:217], v136 offset:41504
	ds_read_b128 v[218:221], v131 offset:55328
	ds_read_b128 v[222:225], v131 offset:59936
	s_waitcnt lgkmcnt(4)
	v_mfma_f32_32x32x16_bf16 v[48:63], v[162:165], v[174:177], v[48:63]
	global_load_dwordx4 v[84:87], v156, s[30:31] offset:384
	v_mfma_f32_32x32x16_bf16 v[32:47], v[162:165], v[206:209], v[32:47]
	global_load_dwordx4 v[92:95], v157, s[30:31] offset:384
	v_mfma_f32_32x32x16_bf16 v[16:31], v[166:169], v[174:177], v[16:31]
	global_load_dwordx4 v[100:103], v158, s[30:31] offset:384
	ds_read_b128 v[226:229], v136 offset:36928
	ds_read_b128 v[230:233], v136 offset:41536
	s_waitcnt vmcnt(3)
	v_mfma_f32_32x32x16_bf16 v[0:15], v[166:169], v[206:209], v[0:15]
	global_load_dwordx4 v[108:111], v159, s[30:31] offset:384
	ds_read_b128 v[234:237], v131 offset:55360
	ds_read_b128 v[238:241], v131 offset:59968
	ds_write_b128 v173, v[64:67]
	s_waitcnt lgkmcnt(5)
	v_mfma_f32_32x32x16_bf16 v[48:63], v[210:213], v[218:221], v[48:63]
	global_load_dwordx4 v[112:115], v160, s[34:35] offset:384
	ds_write_b128 v173, v[68:71] offset:4608
	v_mfma_f32_32x32x16_bf16 v[32:47], v[210:213], v[222:225], v[32:47]
	global_load_dwordx4 v[116:119], v161, s[34:35] offset:384
	ds_write_b128 v173, v[72:75] offset:9216
	v_mfma_f32_32x32x16_bf16 v[16:31], v[214:217], v[218:221], v[16:31]
	global_load_dwordx4 v[120:123], v170, s[34:35] offset:384
	ds_write_b128 v173, v[76:79] offset:13824
	ds_read_b128 v[242:245], v136 offset:36960
	ds_read_b128 v[246:249], v136 offset:41568
	v_mfma_f32_32x32x16_bf16 v[0:15], v[214:217], v[222:225], v[0:15]
	global_load_dwordx4 v[124:127], v171, s[34:35] offset:384
	ds_write_b128 v173, v[80:83] offset:18432
	ds_read_b128 v[250:253], v131 offset:55392
	ds_read_b128 v[144:147], v131 offset:60000
	s_waitcnt lgkmcnt(9)
	v_mfma_f32_32x32x16_bf16 v[48:63], v[226:229], v[234:237], v[48:63]
	ds_write_b128 v173, v[88:91] offset:23040
	v_mfma_f32_32x32x16_bf16 v[32:47], v[226:229], v[238:241], v[32:47]
	ds_write_b128 v173, v[96:99] offset:27648
	v_mfma_f32_32x32x16_bf16 v[16:31], v[230:233], v[234:237], v[16:31]
	ds_write_b128 v173, v[104:107] offset:32256
	v_mfma_f32_32x32x16_bf16 v[0:15], v[230:233], v[238:241], v[0:15]
	s_waitcnt lgkmcnt(0)
	s_barrier
	v_mfma_f32_32x32x16_bf16 v[48:63], v[242:245], v[250:253], v[48:63]
	ds_read_b128 v[162:165], v136
	ds_read_b128 v[166:169], v136 offset:4608
	v_mfma_f32_32x32x16_bf16 v[32:47], v[242:245], v[144:147], v[32:47]
	ds_read_b128 v[174:177], v131 offset:18432
	ds_read_b128 v[206:209], v131 offset:23040
	v_mfma_f32_32x32x16_bf16 v[16:31], v[246:249], v[250:253], v[16:31]
	v_mfma_f32_32x32x16_bf16 v[0:15], v[246:249], v[144:147], v[0:15]
	s_add_u32 s30, s30, 0x100
	s_addc_u32 s31, s31, 0
	s_add_u32 s34, s34, 0x100
	s_addc_u32 s35, s35, 0
	s_add_i32 s7, s7, 2
	s_cmp_lt_u32 s7, 30
	s_cbranch_scc1 .Lp6n_loop
	s_branch .LBB0_302

; template <int MODE>
; DI void attn_item(const u16* __restrict__ Qp, const u16* __restrict__ Kp, const u16* __restrict__ VTp, int q0,
;                   int kt_lo, int kt_hi, u16* __restrict__ Op, int os, float* __restrict__ lsep, int ls, char* lds, int tid) {
;     ...
;     } else {
;       __syncthreads();
;       for (int idx = tid; idx < KT * KCH; idx += 256) {
;         const int r = idx / KCH, ch = idx % KCH;
;         const uint4 v = *(const uint4*)(Kp + (long)(kt * KT + r) * ksd + ch * 8);
;         *(uint4*)(Ks + r * KROW + ch * 16) = v;
;       }
;       for (int idx = tid; idx < 128 * (KT / 8); idx += 256) {
;         const int r = idx / (KT / 8), ch = idx % (KT / 8);
;         const uint4 v = *(const uint4*)(VTp + (long)r * S_ + kt * KT + ch * 8);
;         *(uint4*)(Vs + r * VROW + ch * 16) = v;
;       }
;       __syncthreads();
;     }
.LBB0_451:
	s_sub_i32 s12, s55, s72
	s_lshl_b32 s50, s12, 6
	s_waitcnt vmcnt(63) expcnt(7) lgkmcnt(15)
	s_barrier
	s_and_saveexec_b64 s[12:13], s[8:9]
	s_cbranch_execz .LBB0_456
	s_mov_b64 s[14:15], 0
	v_mov_b32_e32 v64, v169
	v_mov_b32_e32 v65, v213
	v_mov_b32_e32 v66, v152
	v_ashrrev_i32_e32 v67, 31, v66
	v_lshrrev_b32_e32 v67, 28, v67
	v_add_u32_e32 v67, v66, v67
	v_ashrrev_i32_e32 v70, 4, v67
	v_add_u32_e32 v71, s50, v70
	v_lshlrev_b32_e32 v70, 7, v70
	v_mov_b64_e32 v[68:69], s[38:39]
	v_sub_u32_e32 v70, v65, v70
	v_mad_i64_i32 v[68:69], s[48:49], v71, s69, v[68:69]
	v_ashrrev_i32_e32 v71, 31, v70
	v_lshl_add_u64 v[68:69], v[70:71], 1, v[68:69]
	global_load_dwordx4 v[236:239], v[68:69], off offset:1024
	v_add_u32_e32 v72, 0x100, v66
	v_and_b32_e32 v67, -16, v67
	v_mov_b32_e32 v66, v72
	v_add_u32_e32 v252, v64, v67
	v_add_u32_e32 v64, 0x1000, v64
	v_add_u32_e32 v65, 0x800, v65
	v_ashrrev_i32_e32 v67, 31, v66
	v_lshrrev_b32_e32 v67, 28, v67
	v_add_u32_e32 v67, v66, v67
	v_ashrrev_i32_e32 v70, 4, v67
	v_add_u32_e32 v71, s50, v70
	v_lshlrev_b32_e32 v70, 7, v70
	v_mov_b64_e32 v[68:69], s[38:39]
	v_sub_u32_e32 v70, v65, v70
	v_mad_i64_i32 v[68:69], s[48:49], v71, s69, v[68:69]
	v_ashrrev_i32_e32 v71, 31, v70
	v_lshl_add_u64 v[68:69], v[70:71], 1, v[68:69]
	global_load_dwordx4 v[240:243], v[68:69], off offset:1024
	v_add_u32_e32 v72, 0x100, v66
	v_and_b32_e32 v67, -16, v67
	v_mov_b32_e32 v66, v72
	v_add_u32_e32 v253, v64, v67
	v_add_u32_e32 v64, 0x1000, v64
	v_add_u32_e32 v65, 0x800, v65
	v_ashrrev_i32_e32 v67, 31, v66
	v_lshrrev_b32_e32 v67, 28, v67
	v_add_u32_e32 v67, v66, v67
	v_ashrrev_i32_e32 v70, 4, v67
	v_add_u32_e32 v71, s50, v70
	v_lshlrev_b32_e32 v70, 7, v70
	v_mov_b64_e32 v[68:69], s[38:39]
	v_sub_u32_e32 v70, v65, v70
	v_mad_i64_i32 v[68:69], s[48:49], v71, s69, v[68:69]
	v_ashrrev_i32_e32 v71, 31, v70
	v_lshl_add_u64 v[68:69], v[70:71], 1, v[68:69]
	global_load_dwordx4 v[244:247], v[68:69], off offset:1024
	v_add_u32_e32 v72, 0x100, v66
	v_and_b32_e32 v67, -16, v67
	v_mov_b32_e32 v66, v72
	v_add_u32_e32 v154, v64, v67
	v_add_u32_e32 v64, 0x1000, v64
	v_add_u32_e32 v65, 0x800, v65
	v_ashrrev_i32_e32 v67, 31, v66
	v_lshrrev_b32_e32 v67, 28, v67
	v_add_u32_e32 v67, v66, v67
	v_ashrrev_i32_e32 v70, 4, v67
	v_add_u32_e32 v71, s50, v70
	v_lshlrev_b32_e32 v70, 7, v70
	v_mov_b64_e32 v[68:69], s[38:39]
	v_sub_u32_e32 v70, v65, v70
	v_mad_i64_i32 v[68:69], s[48:49], v71, s69, v[68:69]
	v_ashrrev_i32_e32 v71, 31, v70
	v_lshl_add_u64 v[68:69], v[70:71], 1, v[68:69]
	global_load_dwordx4 v[248:251], v[68:69], off offset:1024
	v_add_u32_e32 v72, 0x100, v66
	v_and_b32_e32 v67, -16, v67
	v_mov_b32_e32 v66, v72
	v_add_u32_e32 v205, v64, v67
	v_add_u32_e32 v64, 0x1000, v64
	v_add_u32_e32 v65, 0x800, v65
	s_waitcnt vmcnt(3)
	ds_write_b128 v252, v[236:239]
	s_waitcnt vmcnt(2)
	ds_write_b128 v253, v[240:243]
	s_waitcnt vmcnt(1)
	ds_write_b128 v154, v[244:247]
	s_waitcnt vmcnt(0)
	ds_write_b128 v205, v[248:251]
	s_lshl_b64 s[14:15], s[50:51], 1
	s_add_u32 s14, s97, s14
	s_addc_u32 s15, s54, s15
	s_mov_b64 s[48:49], 0
	v_mov_b32_e32 v64, v214
	v_mov_b32_e32 v65, v213
	v_mov_b32_e32 v66, v152
	v_ashrrev_i32_e32 v67, 31, v66
	v_lshrrev_b32_e32 v67, 29, v67
	v_add_u32_e32 v67, v66, v67
	v_ashrrev_i32_e32 v72, 3, v67
	v_ashrrev_i32_e32 v73, 31, v72
	v_lshlrev_b32_e32 v67, 6, v72
	v_lshlrev_b64 v[68:69], 14, v[72:73]
	v_sub_u32_e32 v70, v65, v67
	v_lshl_add_u64 v[68:69], s[14:15], 0, v[68:69]
	v_ashrrev_i32_e32 v71, 31, v70
	v_lshl_add_u64 v[68:69], v[70:71], 1, v[68:69]
	global_load_dwordx4 v[236:239], v[68:69], off
	v_add_u32_e32 v67, 0x100, v66
	v_mov_b32_e32 v66, v67
	v_lshl_add_u32 v252, v72, 4, v64
	v_add_u32_e32 v64, 0x1000, v64
	v_add_u32_e32 v65, 0x800, v65
	v_ashrrev_i32_e32 v67, 31, v66
	v_lshrrev_b32_e32 v67, 29, v67
	v_add_u32_e32 v67, v66, v67
	v_ashrrev_i32_e32 v72, 3, v67
	v_ashrrev_i32_e32 v73, 31, v72
	v_lshlrev_b32_e32 v67, 6, v72
	v_lshlrev_b64 v[68:69], 14, v[72:73]
	v_sub_u32_e32 v70, v65, v67
	v_lshl_add_u64 v[68:69], s[14:15], 0, v[68:69]
	v_ashrrev_i32_e32 v71, 31, v70
	v_lshl_add_u64 v[68:69], v[70:71], 1, v[68:69]
	global_load_dwordx4 v[240:243], v[68:69], off
	v_add_u32_e32 v67, 0x100, v66
	v_mov_b32_e32 v66, v67
	v_lshl_add_u32 v253, v72, 4, v64
	v_add_u32_e32 v64, 0x1000, v64
	v_add_u32_e32 v65, 0x800, v65
	v_ashrrev_i32_e32 v67, 31, v66
	v_lshrrev_b32_e32 v67, 29, v67
	v_add_u32_e32 v67, v66, v67
	v_ashrrev_i32_e32 v72, 3, v67
	v_ashrrev_i32_e32 v73, 31, v72
	v_lshlrev_b32_e32 v67, 6, v72
	v_lshlrev_b64 v[68:69], 14, v[72:73]
	v_sub_u32_e32 v70, v65, v67
	v_lshl_add_u64 v[68:69], s[14:15], 0, v[68:69]
	v_ashrrev_i32_e32 v71, 31, v70
	v_lshl_add_u64 v[68:69], v[70:71], 1, v[68:69]
	global_load_dwordx4 v[244:247], v[68:69], off
	v_add_u32_e32 v67, 0x100, v66
	v_mov_b32_e32 v66, v67
	v_lshl_add_u32 v154, v72, 4, v64
	v_add_u32_e32 v64, 0x1000, v64
	v_add_u32_e32 v65, 0x800, v65
	v_ashrrev_i32_e32 v67, 31, v66
	v_lshrrev_b32_e32 v67, 29, v67
	v_add_u32_e32 v67, v66, v67
	v_ashrrev_i32_e32 v72, 3, v67
	v_ashrrev_i32_e32 v73, 31, v72
	v_lshlrev_b32_e32 v67, 6, v72
	v_lshlrev_b64 v[68:69], 14, v[72:73]
	v_sub_u32_e32 v70, v65, v67
	v_lshl_add_u64 v[68:69], s[14:15], 0, v[68:69]
	v_ashrrev_i32_e32 v71, 31, v70
	v_lshl_add_u64 v[68:69], v[70:71], 1, v[68:69]
	global_load_dwordx4 v[248:251], v[68:69], off
	v_add_u32_e32 v67, 0x100, v66
	v_mov_b32_e32 v66, v67
	v_lshl_add_u32 v205, v72, 4, v64
	v_add_u32_e32 v64, 0x1000, v64
	v_add_u32_e32 v65, 0x800, v65
	s_waitcnt vmcnt(3)
	ds_write_b128 v252, v[236:239]
	s_waitcnt vmcnt(2)
	ds_write_b128 v253, v[240:243]
	s_waitcnt vmcnt(1)
	ds_write_b128 v154, v[244:247]
	s_waitcnt vmcnt(0)
	ds_write_b128 v205, v[248:251]

; template <class LA>
; DI void gemm_tile(const LA& la, int m0, const u16* __restrict__ Bm, long ldb, int K, f32x16 (&acc)[2][2], char* lds, int tid) {
;     ...
;   const int arow = (wm * 64 + (lane & 31)) * 144 + (lane >> 5) * 16;
;   const int brow = 18432 + (wn * 64 + (lane & 31)) * 144 + (lane >> 5) * 16;
;   char* lds0 = lds;
;   char* lds1 = lds + 36864;
;   __syncthreads();
;   GT_LOAD(p, 0)
;   if (nk > 1) { GT_LOAD(q, 64) }
;   GT_STORE(p, lds0)
;   __syncthreads();
; template <int MASK>
; __global__ void __launch_bounds__(256, 2) fwd_megakernel_t(Params p) {
;     ...
;       for (int step = 0;; step++) {
;         int mt, nt;
;         if (!next_tile(step, 128, 85, mt, nt)) break;
;         if (nt >= 85) continue;
;         const int m0 = mt * 128, n0 = nt * 128;
;         f32x16 acc[2][2];
;         zero_acc(acc);
;         gemm_tile(LoadPlain{xb, 2048}, m0, w_in + (size_t)n0 * 2048, 2048, 2048, acc, lds, tid);
.LBB0_730:
	s_andn2_b64 vcc, exec, s[4:5]
	s_mov_b32 s8, 14
	s_cbranch_vccnz .LBB0_772
	s_cmpk_gt_i32 s25, 0x54
	s_mov_b32 s8, 16
	s_cbranch_scc1 .LBB0_772
	s_lshl_b32 s6, s25, 7
	s_lshl_b32 s10, s24, 7
	s_ashr_i32 s7, s6, 31
	s_lshl_b64 s[4:5], s[6:7], 12
	v_add_u32_e32 v0, s10, v128
	v_lshl_add_u64 v[2:3], v[132:133], 0, s[4:5]
	v_ashrrev_i32_e32 v1, 31, v0
	s_mov_b32 s7, 0x20000
	v_lshlrev_b64 v[20:21], 12, v[0:1]
	v_add_co_u32_e32 v10, vcc, s7, v2
	v_lshl_add_u64 v[0:1], s[82:83], 0, v[20:21]
	v_lshl_add_u64 v[22:23], v[20:21], 0, s[42:43]
	s_mov_b64 s[8:9], 0x40000
	v_addc_co_u32_e32 v11, vcc, 0, v3, vcc
	s_mov_b32 s7, 0x40000
	v_lshl_add_u64 v[4:5], v[0:1], 0, v[150:151]
	v_lshl_add_u64 v[0:1], s[82:83], 0, v[22:23]
	v_lshl_add_u64 v[24:25], v[20:21], 0, s[8:9]
	v_add_co_u32_e32 v12, vcc, s7, v2
	s_mov_b64 s[8:9], 0x60000
	v_lshl_add_u64 v[6:7], v[0:1], 0, v[150:151]
	v_lshl_add_u64 v[0:1], s[82:83], 0, v[24:25]
	v_addc_co_u32_e32 v13, vcc, 0, v3, vcc
	s_mov_b32 s7, 0x60000
	v_lshl_add_u64 v[26:27], v[20:21], 0, s[8:9]
	v_lshl_add_u64 v[8:9], v[0:1], 0, v[150:151]
	v_add_co_u32_e32 v14, vcc, s7, v2
	v_lshl_add_u64 v[0:1], s[82:83], 0, v[26:27]
	s_nop 0
	v_addc_co_u32_e32 v15, vcc, 0, v3, vcc
	v_lshl_add_u64 v[16:17], v[0:1], 0, v[150:151]
	s_barrier
	global_load_dwordx4 v[64:67], v[4:5], off
	global_load_dwordx4 v[68:71], v[6:7], off
	global_load_dwordx4 v[72:75], v[8:9], off
	global_load_dwordx4 v[88:91], v[2:3], off
	global_load_dwordx4 v[84:87], v[10:11], off
	global_load_dwordx4 v[92:95], v[12:13], off
	global_load_dwordx4 v[100:103], v[14:15], off
	global_load_dwordx4 v[76:79], v[16:17], off
	global_load_dwordx4 v[80:83], v[4:5], off offset:128
	global_load_dwordx4 v[96:99], v[6:7], off offset:128
	global_load_dwordx4 v[104:107], v[8:9], off offset:128
	global_load_dwordx4 v[108:111], v[16:17], off offset:128
	global_load_dwordx4 v[120:123], v[2:3], off offset:128
	global_load_dwordx4 v[112:115], v[10:11], off offset:128
	global_load_dwordx4 v[116:119], v[12:13], off offset:128
	global_load_dwordx4 v[124:127], v[14:15], off offset:128
	v_mov_b32_e32 v0, 0
	s_mov_b32 s7, 0
	v_add_u32_e32 v172, v129, v130
	v_mov_b32_e32 v1, v0
	v_mov_b32_e32 v2, v0
	v_mov_b32_e32 v3, v0
	v_mov_b32_e32 v4, v0
	v_mov_b32_e32 v5, v0
	v_mov_b32_e32 v6, v0
	v_mov_b32_e32 v7, v0
	v_mov_b32_e32 v8, v0
	v_mov_b32_e32 v9, v0
	v_mov_b32_e32 v10, v0
	v_mov_b32_e32 v11, v0
	v_mov_b32_e32 v12, v0
	v_mov_b32_e32 v13, v0
	v_mov_b32_e32 v14, v0
	v_mov_b32_e32 v15, v0
	v_mov_b32_e32 v16, v0
	v_mov_b32_e32 v17, v0
	v_mov_b32_e32 v18, v0
	v_mov_b32_e32 v19, v0
	s_waitcnt vmcnt(32)
	v_lshl_add_u64 v[144:145], v[142:143], 0, s[4:5]
	v_lshl_add_u64 v[146:147], s[76:77], 0, v[20:21]
	v_lshl_add_u64 v[156:157], s[76:77], 0, v[26:27]
	v_lshl_add_u64 v[158:159], s[76:77], 0, v[24:25]
	v_lshl_add_u64 v[160:161], s[76:77], 0, v[22:23]
	v_mov_b32_e32 v20, v0
	v_mov_b32_e32 v21, v0
	v_mov_b32_e32 v22, v0
	v_mov_b32_e32 v23, v0
	v_mov_b32_e32 v24, v0
	v_mov_b32_e32 v25, v0
	v_mov_b32_e32 v26, v0
	v_mov_b32_e32 v27, v0
	v_mov_b32_e32 v28, v0
	v_mov_b32_e32 v29, v0
	v_mov_b32_e32 v30, v0
	v_mov_b32_e32 v31, v0
	s_waitcnt vmcnt(16)
	v_mov_b32_e32 v32, v0
	v_mov_b32_e32 v33, v0
	v_mov_b32_e32 v34, v0
	v_mov_b32_e32 v35, v0
	v_mov_b32_e32 v36, v0
	v_mov_b32_e32 v37, v0
	v_mov_b32_e32 v38, v0
	v_mov_b32_e32 v39, v0
	v_mov_b32_e32 v40, v0
	v_mov_b32_e32 v41, v0
	v_mov_b32_e32 v42, v0
	v_mov_b32_e32 v43, v0
	v_mov_b32_e32 v44, v0
	v_mov_b32_e32 v45, v0
	v_mov_b32_e32 v46, v0
	v_mov_b32_e32 v47, v0
	v_mov_b32_e32 v48, v0
	v_mov_b32_e32 v49, v0
	v_mov_b32_e32 v50, v0
	v_mov_b32_e32 v51, v0
	v_mov_b32_e32 v52, v0
	v_mov_b32_e32 v53, v0
	v_mov_b32_e32 v54, v0
	v_mov_b32_e32 v55, v0
	v_mov_b32_e32 v56, v0
	v_mov_b32_e32 v57, v0
	v_mov_b32_e32 v58, v0
	v_mov_b32_e32 v59, v0
	v_mov_b32_e32 v60, v0
	v_mov_b32_e32 v61, v0
	v_mov_b32_e32 v62, v0
	v_mov_b32_e32 v63, v0
	s_waitcnt vmcnt(12)
	ds_write_b128 v172, v[88:91] offset:18432
	s_waitcnt vmcnt(11)
	ds_write_b128 v172, v[84:87] offset:23040
	s_waitcnt vmcnt(10)
	ds_write_b128 v172, v[92:95] offset:27648
	s_waitcnt vmcnt(9)
	ds_write_b128 v172, v[100:103] offset:32256
	ds_write_b128 v172, v[64:67]
	ds_write_b128 v172, v[68:71] offset:4608
	ds_write_b128 v172, v[72:75] offset:9216
	s_waitcnt vmcnt(8)
	ds_write_b128 v172, v[76:79] offset:13824
	s_waitcnt lgkmcnt(0)
	s_barrier
	v_lshl_add_u64 v[162:163], v[146:147], 0, v[140:141]
	v_lshl_add_u64 v[164:165], v[144:145], 0, v[140:141]
	v_add_co_u32_e32 v162, vcc, 0x84e0000, v162
	s_nop 1
	v_addc_co_u32_e32 v163, vcc, 0, v163, vcc
	s_nop 0
	v_readfirstlane_b32 s30, v162
	v_readfirstlane_b32 s31, v163
	v_readfirstlane_b32 s34, v164
	v_readfirstlane_b32 s35, v165
	s_nop 1
	v_subrev_u32_e32 v156, s30, v162
	v_subrev_u32_e32 v160, s34, v164
	v_add_u32_e32 v157, 0x20000, v156
	v_add_u32_e32 v158, 0x40000, v156
	v_add_u32_e32 v159, 0x60000, v156
	v_add_u32_e32 v161, 0x20000, v160
	v_add_u32_e32 v170, 0x40000, v160
	v_add_u32_e32 v171, 0x60000, v160
	ds_read_b128 v[162:165], v134
	ds_read_b128 v[166:169], v134 offset:4608
	ds_read_b128 v[174:177], v135 offset:18432
	ds_read_b128 v[206:209], v135 offset:23040
; template <class LA>
; DI void gemm_tile(const LA& la, int m0, const u16* __restrict__ Bm, long ldb, int K, f32x16 (&acc)[2][2], char* lds, int tid) {
;     ...
;   const int arow = (wm * 64 + (lane & 31)) * 144 + (lane >> 5) * 16;
;   const int brow = 18432 + (wn * 64 + (lane & 31)) * 144 + (lane >> 5) * 16;
;   char* lds0 = lds;
;   char* lds1 = lds + 36864;
;   __syncthreads();
;   GT_LOAD(p, 0)
;   if (nk > 1) { GT_LOAD(q, 64) }
;   GT_STORE(p, lds0)
;   __syncthreads();
; #pragma unroll 1
;   for (int kt = 0; kt < nk; kt += 2) {
;     if (kt + 2 < nk) { GT_LOAD(p, (kt + 2) * 64) }
;     GT_COMPUTE(lds0)
;     if (kt + 1 < nk) { GT_STORE(q, lds1) }
;     __syncthreads();
;     if (kt + 1 >= nk) break;
;     if (kt + 3 < nk) { GT_LOAD(q, (kt + 3) * 64) }
;     GT_COMPUTE(lds1)
;     if (kt + 2 < nk) { GT_STORE(p, lds0) }
;     __syncthreads();
;   }
.Lp1n_loop:
	ds_read_b128 v[210:213], v134 offset:32
	ds_read_b128 v[214:217], v134 offset:4640
	ds_read_b128 v[218:221], v135 offset:18464
	ds_read_b128 v[222:225], v135 offset:23072
	s_waitcnt lgkmcnt(4)
	v_mfma_f32_32x32x16_bf16 v[48:63], v[162:165], v[174:177], v[48:63]
	global_load_dwordx4 v[64:67], v156, s[30:31] offset:256
	s_waitcnt vmcnt(8)
	ds_write_b128 v172, v[80:83] offset:36864
	v_mfma_f32_32x32x16_bf16 v[32:47], v[162:165], v[206:209], v[32:47]
	global_load_dwordx4 v[68:71], v157, s[30:31] offset:256
	s_waitcnt vmcnt(8)
	ds_write_b128 v172, v[96:99] offset:41472
	v_mfma_f32_32x32x16_bf16 v[16:31], v[166:169], v[174:177], v[16:31]
	ds_read_b128 v[226:229], v134 offset:64
	ds_read_b128 v[230:233], v134 offset:4672
	global_load_dwordx4 v[72:75], v158, s[30:31] offset:256
	s_waitcnt vmcnt(8)
	ds_write_b128 v172, v[104:107] offset:46080
	v_mfma_f32_32x32x16_bf16 v[0:15], v[166:169], v[206:209], v[0:15]
	ds_read_b128 v[234:237], v135 offset:18496
	ds_read_b128 v[238:241], v135 offset:23104
	global_load_dwordx4 v[76:79], v159, s[30:31] offset:256
	s_waitcnt vmcnt(8)
	ds_write_b128 v172, v[108:111] offset:50688
	s_waitcnt lgkmcnt(8)
	v_mfma_f32_32x32x16_bf16 v[48:63], v[210:213], v[218:221], v[48:63]
	global_load_dwordx4 v[88:91], v160, s[34:35] offset:256
	s_waitcnt vmcnt(8)
	ds_write_b128 v172, v[120:123] offset:55296
	v_mfma_f32_32x32x16_bf16 v[32:47], v[210:213], v[222:225], v[32:47]
	global_load_dwordx4 v[84:87], v161, s[34:35] offset:256
	s_waitcnt vmcnt(8)
	ds_write_b128 v172, v[112:115] offset:59904
	v_mfma_f32_32x32x16_bf16 v[16:31], v[214:217], v[218:221], v[16:31]
	ds_read_b128 v[242:245], v134 offset:96
	ds_read_b128 v[246:249], v134 offset:4704
	global_load_dwordx4 v[92:95], v170, s[34:35] offset:256
	s_waitcnt vmcnt(8)
	ds_write_b128 v172, v[116:119] offset:64512
	v_mfma_f32_32x32x16_bf16 v[0:15], v[214:217], v[222:225], v[0:15]
	ds_read_b128 v[250:253], v135 offset:18528
	ds_read_b128 v[144:147], v135 offset:23136
	global_load_dwordx4 v[100:103], v171, s[34:35] offset:256
	s_waitcnt vmcnt(8)
	ds_write_b128 v153, v[124:127] offset:13824
	s_waitcnt lgkmcnt(9)
	v_mfma_f32_32x32x16_bf16 v[48:63], v[226:229], v[234:237], v[48:63]
	v_mfma_f32_32x32x16_bf16 v[32:47], v[226:229], v[238:241], v[32:47]
	v_mfma_f32_32x32x16_bf16 v[16:31], v[230:233], v[234:237], v[16:31]
	v_mfma_f32_32x32x16_bf16 v[0:15], v[230:233], v[238:241], v[0:15]
	s_waitcnt lgkmcnt(0)
	s_barrier
	v_mfma_f32_32x32x16_bf16 v[48:63], v[242:245], v[250:253], v[48:63]
	ds_read_b128 v[162:165], v134 offset:36864
	ds_read_b128 v[166:169], v134 offset:41472
	v_mfma_f32_32x32x16_bf16 v[32:47], v[242:245], v[144:147], v[32:47]
	ds_read_b128 v[174:177], v135 offset:55296
	ds_read_b128 v[206:209], v135 offset:59904
	v_mfma_f32_32x32x16_bf16 v[16:31], v[246:249], v[250:253], v[16:31]
	v_mfma_f32_32x32x16_bf16 v[0:15], v[246:249], v[144:147], v[0:15]
	ds_read_b128 v[210:213], v134 offset:36896
	ds_read_b128 v[214:217], v134 offset:41504
	ds_read_b128 v[218:221], v135 offset:55328
	ds_read_b128 v[222:225], v135 offset:59936
	s_waitcnt lgkmcnt(4)
	v_mfma_f32_32x32x16_bf16 v[48:63], v[162:165], v[174:177], v[48:63]
	global_load_dwordx4 v[80:83], v156, s[30:31] offset:384
	s_waitcnt vmcnt(8)
	ds_write_b128 v172, v[64:67]
	v_mfma_f32_32x32x16_bf16 v[32:47], v[162:165], v[206:209], v[32:47]
	global_load_dwordx4 v[96:99], v157, s[30:31] offset:384
	s_waitcnt vmcnt(8)
	ds_write_b128 v172, v[68:71] offset:4608
	v_mfma_f32_32x32x16_bf16 v[16:31], v[166:169], v[174:177], v[16:31]
	ds_read_b128 v[226:229], v134 offset:36928
	ds_read_b128 v[230:233], v134 offset:41536
	global_load_dwordx4 v[104:107], v158, s[30:31] offset:384
	s_waitcnt vmcnt(8)
	ds_write_b128 v172, v[72:75] offset:9216
	v_mfma_f32_32x32x16_bf16 v[0:15], v[166:169], v[206:209], v[0:15]
	ds_read_b128 v[234:237], v135 offset:55360
	ds_read_b128 v[238:241], v135 offset:59968
	global_load_dwordx4 v[108:111], v159, s[30:31] offset:384
	s_waitcnt vmcnt(8)
	ds_write_b128 v172, v[76:79] offset:13824
	s_waitcnt lgkmcnt(8)
	v_mfma_f32_32x32x16_bf16 v[48:63], v[210:213], v[218:221], v[48:63]
	global_load_dwordx4 v[120:123], v160, s[34:35] offset:384
	s_waitcnt vmcnt(8)
	ds_write_b128 v172, v[88:91] offset:18432
	v_mfma_f32_32x32x16_bf16 v[32:47], v[210:213], v[222:225], v[32:47]
	global_load_dwordx4 v[112:115], v161, s[34:35] offset:384
	s_waitcnt vmcnt(8)
	ds_write_b128 v172, v[84:87] offset:23040
	v_mfma_f32_32x32x16_bf16 v[16:31], v[214:217], v[218:221], v[16:31]
	ds_read_b128 v[242:245], v134 offset:36960
	ds_read_b128 v[246:249], v134 offset:41568
	global_load_dwordx4 v[116:119], v170, s[34:35] offset:384
	s_waitcnt vmcnt(8)
	ds_write_b128 v172, v[92:95] offset:27648
	v_mfma_f32_32x32x16_bf16 v[0:15], v[214:217], v[222:225], v[0:15]
	ds_read_b128 v[250:253], v135 offset:55392
	ds_read_b128 v[144:147], v135 offset:60000
	global_load_dwordx4 v[124:127], v171, s[34:35] offset:384
	s_waitcnt vmcnt(8)
	ds_write_b128 v172, v[100:103] offset:32256
	s_waitcnt lgkmcnt(9)
	v_mfma_f32_32x32x16_bf16 v[48:63], v[226:229], v[234:237], v[48:63]
	v_mfma_f32_32x32x16_bf16 v[32:47], v[226:229], v[238:241], v[32:47]
	v_mfma_f32_32x32x16_bf16 v[16:31], v[230:233], v[234:237], v[16:31]
	v_mfma_f32_32x32x16_bf16 v[0:15], v[230:233], v[238:241], v[0:15]
	s_waitcnt lgkmcnt(0)
	s_barrier
	v_mfma_f32_32x32x16_bf16 v[48:63], v[242:245], v[250:253], v[48:63]
	ds_read_b128 v[162:165], v134
	ds_read_b128 v[166:169], v134 offset:4608
	v_mfma_f32_32x32x16_bf16 v[32:47], v[242:245], v[144:147], v[32:47]
	ds_read_b128 v[174:177], v135 offset:18432
	ds_read_b128 v[206:209], v135 offset:23040
	v_mfma_f32_32x32x16_bf16 v[16:31], v[246:249], v[250:253], v[16:31]
	v_mfma_f32_32x32x16_bf16 v[0:15], v[246:249], v[144:147], v[0:15]
	s_add_u32 s30, s30, 0x100
	s_addc_u32 s31, s31, 0
	s_add_u32 s34, s34, 0x100
	s_addc_u32 s35, s35, 0
	s_add_i32 s7, s7, 2
	s_cmp_lt_u32 s7, 30
	s_cbranch_scc1 .Lp1n_loop
	s_branch .LBB0_734
